# rwkv_apply loader waves run at raised priority (s_setprio 2) so their DMA issue is not delayed by the consumer wave on the same SIMD
# baseline (speedup 1.0000x reference)
.LBB0_1025:
	s_and_b64 vcc, exec, s[0:1]
	s_cbranch_vccz .LBB0_1045
	s_setprio 2
	s_sub_i32 s3, s57, 4
	s_mul_i32 s15, s2, 0x3200
	s_add_u32 s4, s52, s15
	s_addc_u32 s5, s53, 0
	s_add_u32 s4, s4, 0x100000
	s_addc_u32 s5, s5, 0
	s_lshl_b32 s10, s3, 10
	s_add_u32 s4, s4, s10
	s_addc_u32 s5, s5, 0
	s_lshr_b32 s15, s2, 4
	s_mul_i32 s15, s15, 0x5400000
	s_and_b32 s20, s2, 15
	s_lshl_b32 s20, s20, 7
	s_add_u32 s15, s15, s20
	s_add_u32 s6, s52, s15
	s_addc_u32 s7, s53, 0
	s_add_u32 s6, s6, 0xdffd400
	s_addc_u32 s7, s7, 0
	v_lshlrev_b32_e32 v0, 4, v146
	s_cmp_eq_u32 s3, 0
	s_cbranch_scc1 .Lld_w0
	s_sub_i32 s15, s3, 1
	s_lshl_b32 s20, s15, 6
	v_add_u32_e32 v1, s20, v146
	v_lshrrev_b32_e32 v2, 3, v1
	v_and_b32_e32 v1, 7, v1
	v_mul_u32_u24_e32 v2, 0x5400, v2
	v_lshl_add_u32 v1, v1, 4, v2
	s_mov_b32 s8, 0x54000
	s_lshl_b32 s9, s15, 10
	s_add_u32 s9, s9, 0x3200
	s_mov_b64 s[12:13], -1
	s_cmp_eq_u32 s3, 3
	s_cselect_b32 s12, 0xff, s12
	s_cselect_b32 s13, 0, s13
	s_branch .Lld_wdone

.Lld_bar:
	s_barrier
	s_and_b32 s15, s14, 1
	s_lshl_b32 s15, s15, 12
	s_add_u32 s15, s15, 119808
	v_add_u32_e32 v4, s15, v3
	ds_read_b128 v[8:11], v4
	s_lshl_b32 s15, s14, 16
	s_add_u32 s66, s68, s15
	s_addc_u32 s67, s69, 0
	s_cmp_eq_u32 s14, 0
	s_cselect_b32 s70, s72, -1
	s_cselect_b32 s71, s73, -1
	s_waitcnt lgkmcnt(0)
	s_mov_b64 exec, s[70:71]
	global_store_dwordx4 v5, v[8:11], s[66:67]
	s_mov_b64 exec, -1
	s_add_u32 s14, s14, 1
	s_cmp_lt_u32 s14, 128
	s_cbranch_scc1 .Lld_loop
	s_setprio 0
